# grid barrier leader exit: XGEN increment and the waits for the fire-and-forget TOPGEN/XGEN atomics dropped
# speedup vs baseline: 1.0162x; 1.0022x over previous
.LBB0_166:
	s_or_b64 exec, exec, s[8:9]
	s_mov_b64 s[8:9], exec
	v_mbcnt_lo_u32_b32 v0, s8, 0
	v_mbcnt_hi_u32_b32 v0, s9, v0
	v_cmp_eq_u32_e32 vcc, 0, v0
	s_and_saveexec_b64 s[12:13], vcc
	s_cbranch_execz .LBB0_168
	s_bcnt1_i32_b64 s8, s[8:9]
	v_mov_b32_e32 v0, 0x2000
	v_mov_b32_e32 v1, s8
.LBB0_168:
	s_or_b64 exec, exec, s[12:13]
.LBB0_169:
	s_or_b64 exec, exec, s[0:1]
	s_waitcnt lgkmcnt(0)
	s_barrier

.LBB0_243:
	s_or_b64 exec, exec, s[6:7]
	s_mov_b64 s[6:7], exec
	v_mbcnt_lo_u32_b32 v0, s6, 0
	v_mbcnt_hi_u32_b32 v0, s7, v0
	v_cmp_eq_u32_e32 vcc, 0, v0
	s_and_saveexec_b64 s[8:9], vcc
	s_cbranch_execz .LBB0_245
	s_bcnt1_i32_b64 s6, s[6:7]
	v_mov_b32_e32 v0, 0x2000
	v_mov_b32_e32 v1, s6
.LBB0_245:
	s_or_b64 exec, exec, s[8:9]
.LBB0_246:
	s_or_b64 exec, exec, s[0:1]
	s_waitcnt lgkmcnt(0)
	s_barrier

.LBB0_248:
	s_or_b64 exec, exec, s[16:17]
.LBB0_249:
	s_or_b64 exec, exec, s[0:1]
	s_waitcnt lgkmcnt(0)
	s_barrier

.LBB0_332:
	s_or_b64 exec, exec, s[10:11]
	s_mov_b64 s[10:11], exec
	v_mbcnt_lo_u32_b32 v0, s10, 0
	v_mbcnt_hi_u32_b32 v0, s11, v0
	v_cmp_eq_u32_e32 vcc, 0, v0
	s_and_saveexec_b64 s[16:17], vcc
	s_cbranch_execz .LBB0_334
	s_bcnt1_i32_b64 s4, s[10:11]
	v_mov_b32_e32 v0, s4
	v_readlane_b32 s4, v254, 12
	v_readlane_b32 s5, v254, 13
	s_nop 4
.LBB0_334:
	s_or_b64 exec, exec, s[16:17]
.LBB0_335:
	s_or_b64 exec, exec, s[0:1]
	s_waitcnt lgkmcnt(0)
	s_barrier

.LBB0_533:
	s_or_b64 exec, exec, s[10:11]
	s_mov_b64 s[10:11], exec
	v_mbcnt_lo_u32_b32 v0, s10, 0
	v_mbcnt_hi_u32_b32 v0, s11, v0
	v_cmp_eq_u32_e32 vcc, 0, v0
	s_and_saveexec_b64 s[16:17], vcc
	s_cbranch_execz .LBB0_535
	s_bcnt1_i32_b64 s5, s[10:11]
	v_readlane_b32 s10, v254, 12
	v_mov_b32_e32 v0, s5
	v_readlane_b32 s11, v254, 13
	s_nop 4
.LBB0_535:
	s_or_b64 exec, exec, s[16:17]
.LBB0_536:
	s_or_b64 exec, exec, s[0:1]
	s_waitcnt lgkmcnt(0)
	s_barrier

.LBB0_1498:
	s_or_b64 exec, exec, s[16:17]
.LBB0_1499:
	s_or_b64 exec, exec, s[0:1]
	s_waitcnt lgkmcnt(0)
	s_barrier

.LBB0_1566:
	s_or_b64 exec, exec, s[16:17]
.LBB0_1567:
	s_or_b64 exec, exec, s[0:1]
	s_waitcnt lgkmcnt(0)
	s_barrier

.LBB0_1641:
	s_or_b64 exec, exec, s[16:17]
.LBB0_1642:
	s_or_b64 exec, exec, s[0:1]
	s_waitcnt lgkmcnt(0)
	s_barrier

.LBB0_1830:
	s_or_b64 exec, exec, s[10:11]
	s_mov_b64 s[10:11], exec
	v_mbcnt_lo_u32_b32 v0, s10, 0
	v_mbcnt_hi_u32_b32 v0, s11, v0
	v_cmp_eq_u32_e32 vcc, 0, v0
	s_and_saveexec_b64 s[16:17], vcc
	s_cbranch_execz .LBB0_248
	s_bcnt1_i32_b64 s4, s[10:11]
	v_mov_b32_e32 v0, s4
	v_readlane_b32 s4, v254, 12
	v_readlane_b32 s5, v254, 13
	s_nop 4
	s_branch .LBB0_248
